# scan: idle wave prefetches its quarter of G + neighbour H into L2 ahead of the scanning wave (cross-CU L2 warming, LDS-paced); attention: constant bias hoisted, prologue drain removed
# speedup vs baseline: 1.0072x; 1.0005x over previous
; DI void attn_block2(const Params& p, int bh, int cp, char* lds) {
;     int tid = threadIdx.x; asm volatile("" : "+v"(tid));
;     const int lane = tid & 63, wave = __builtin_amdgcn_readfirstlane(tid >> 6);
;     const u16* proj = (const u16*)(p.ws + W_PROJ);
;     const int b = bh >> 3, h = bh & 7, c0 = 2 * cp, cq = c0 + (wave >> 1);
;     const int qposA = (wave & 1) * 32 + (lane & 15); const int qrowA = b * 8192 + cq * 64 + qposA;
;     float* tab = (float*)(lds + 49152);
;     __syncthreads();
;     for (int i = tid; i < 257; i += 256) tab[i] = p.relb[h * 257 + i] * LOG2E;
;     QG A, B;
;     { const u16* qp = proj + (size_t)qrowA * NC + C_Q + h * 64 + 8 * (lane >> 4); A.q0 = *(const bf16x8*)qp; A.q1 = *(const bf16x8*)(qp + 32);
;       const u16* qb = qp + (size_t)16 * NC; B.q0 = *(const bf16x8*)qb; B.q1 = *(const bf16x8*)(qb + 32); }
;     A.m = -INFINITY; A.l = 0.f; B.m = -INFINITY; B.l = 0.f;
; #pragma unroll
;     for (int dt = 0; dt < 4; ++dt) { A.o[dt] = (f32x4){0.f, 0.f, 0.f, 0.f}; B.o[dt] = (f32x4){0.f, 0.f, 0.f, 0.f}; }
;     unsigned soff[2];
; #pragma unroll
;     for (int i = 0; i < 2; ++i) { const int row = 8 * (i * 4 + wave) + (lane >> 3); const int ch = (lane & 7) ^ ((row >> 1) & 7); soff[i] = (unsigned)(row * NC + ch * 8); }
;     const u16* kbase = proj + (size_t)(b * 8192) * NC + h * 64;
;     ...
;     const int lo = c0 >= 8 ? c0 - 8 : 0, hi = c0 + 1;
;     __syncthreads();
;     ASTAGE2(0, lo); ASTAGE2(1, lo + 1);
;     int buf = 0;
;     for (int kc = lo; kc <= hi; ++kc) {
;         if (kc < hi) asm volatile("s_waitcnt vmcnt(4) lgkmcnt(0)" ::: "memory"); else asm volatile("s_waitcnt vmcnt(0) lgkmcnt(0)" ::: "memory");
;         __builtin_amdgcn_s_barrier();
;         asm volatile("" ::: "memory");
;         const int nb2 = buf >= 1 ? buf - 1 : 2;
;         if (kc + 2 <= hi) ASTAGE2(nb2, kc + 2);
.LBB0_396:
	s_or_b64 exec, exec, s[6:7]
	s_sub_i32 s3, s33, 32
	s_and_b32 s2, s3, -2
	s_ashr_i32 s30, s4, 6
	s_sub_i32 s36, 0x7e, s2
	s_ashr_i32 s6, s4, 7
	s_add_i32 s4, s6, s36
	s_lshl_b32 s7, s30, 5
	s_and_b32 s7, s7, 32
	v_and_b32_e32 v2, 15, v82
	s_lshl_b32 s4, s4, 6
	v_or_b32_e32 v3, s7, v2
	s_add_i32 s4, s4, s83
	v_or_b32_e32 v83, s4, v3
	v_mov_b64_e32 v[4:5], s[68:69]
	v_mad_i64_i32 v[4:5], s[28:29], v83, s43, v[4:5]
	s_lshl_b32 s4, s88, 7
	v_lshl_add_u64 v[4:5], v[4:5], 0, s[4:5]
	v_and_b32_e32 v158, 48, v82
	v_lshl_add_u64 v[4:5], v[4:5], 0, v[158:159]
	s_mov_b32 s28, 0x21000
	global_load_dwordx4 v[18:21], v[4:5], off
	global_load_dwordx4 v[22:25], v[4:5], off offset:64
	v_add_co_u32_e32 v4, vcc, s28, v4
	v_bfe_u32 v3, v82, 3, 3
	s_nop 0
	v_addc_co_u32_e32 v5, vcc, 0, v5, vcc
	v_lshl_or_b32 v3, s30, 3, v3
	s_movk_i32 s28, 0x1080
	s_add_u32 s4, s86, s4
	global_load_dwordx4 v[26:29], v[4:5], off
	global_load_dwordx4 v[30:33], v[4:5], off offset:64
	v_lshrrev_b32_e32 v4, 1, v3
	v_mul_lo_u32 v3, v3, s28
	s_addc_u32 s37, s87, 0
	s_sub_i32 s28, 0x76, s2
	s_cmpk_lt_u32 s3, 0x78
	s_cselect_b32 s89, s28, 0
	s_mul_i32 s28, s89, 0x42000
	v_xor_b32_e32 v4, v4, v82
	s_ashr_i32 s29, s28, 31
	v_lshlrev_b32_e32 v4, 3, v4
	s_lshl_b64 s[28:29], s[28:29], 1
	v_and_or_b32 v158, v4, 56, v3
	s_add_u32 s28, s4, s28
	s_addc_u32 s29, s37, s29
	s_lshl_b32 s30, s30, 10
	v_lshlrev_b64 v[4:5], 1, v[158:159]
	v_lshl_add_u64 v[6:7], s[28:29], 0, v[4:5]
	s_add_i32 s90, s30, 0
	v_lshl_add_u64 v[8:9], v[6:7], 0, s[0:1]
	s_mov_b32 m0, s90
	v_add_u32_e32 v84, 0x21000, v158
	s_waitcnt lgkmcnt(0)
	s_barrier
	global_load_lds_dwordx4 v[8:9], off
	v_lshl_add_u64 v[6:7], v[6:7], 0, s[8:9]
	s_add_i32 m0, s90, 0x6000
	v_mov_b32_e32 v85, v159
	global_load_lds_dwordx4 v[6:7], off
	v_lshlrev_b64 v[6:7], 1, v[84:85]
	v_lshl_add_u64 v[8:9], s[28:29], 0, v[6:7]
	v_lshl_add_u64 v[10:11], v[8:9], 0, s[0:1]
	s_add_i32 m0, s90, 0x1000
	v_lshl_add_u64 v[8:9], v[8:9], 0, s[8:9]
	global_load_lds_dwordx4 v[10:11], off
	s_add_i32 m0, s90, 0x7000
	s_add_u32 s28, s28, 0x84000
	s_addc_u32 s29, s29, 0
	v_lshl_add_u64 v[4:5], s[28:29], 0, v[4:5]
	global_load_lds_dwordx4 v[8:9], off
	v_lshl_add_u64 v[8:9], v[4:5], 0, s[0:1]
	s_add_i32 m0, s90, 0x2000
	v_lshl_add_u64 v[4:5], v[4:5], 0, s[8:9]
	global_load_lds_dwordx4 v[8:9], off
	s_add_i32 m0, s90, 0x8000
	s_sub_i32 s91, 0x7f, s2
	global_load_lds_dwordx4 v[4:5], off
	v_lshl_add_u64 v[4:5], s[28:29], 0, v[6:7]
	v_lshl_add_u64 v[6:7], v[4:5], 0, s[0:1]
	s_add_i32 m0, s90, 0x3000
	v_lshl_add_u64 v[4:5], v[4:5], 0, s[8:9]
	global_load_lds_dwordx4 v[6:7], off
	s_add_i32 m0, s90, 0x9000
	v_and_b32_e32 v106, 63, v82
	global_load_lds_dwordx4 v[4:5], off
	s_cmp_le_i32 s89, s91
	s_mov_b32 s92, 0
	s_cbranch_scc0 .LBB0_416
	ds_read_b32 v207, v159 offset:50176
	v_lshrrev_b32_e32 v4, 4, v106
	v_bfe_u32 v5, v82, 1, 3
	v_lshrrev_b32_e32 v3, 1, v82
	v_bitop3_b32 v5, v4, v5, 4 bitop3:0x36
	s_lshl_b32 s28, s6, 6
	v_bitop3_b32 v6, v3, v4, 7 bitop3:0x6c
	v_lshlrev_b32_e32 v108, 4, v5
	v_lshlrev_b32_e32 v4, 2, v4
	v_lshrrev_b32_e32 v5, 2, v2
	s_or_b32 s7, s28, s7
	v_lshlrev_b32_e32 v107, 4, v6
	v_lshlrev_b32_e32 v6, 3, v106
	v_or_b32_e32 v5, v4, v5
	s_addk_i32 s7, 0x1f90
	v_and_b32_e32 v6, 8, v6
	v_lshlrev_b32_e32 v110, 7, v5
	v_lshrrev_b32_e32 v5, 1, v5
	v_lshl_add_u32 v115, v2, 7, 0
	v_add_u32_e32 v2, s7, v2
	v_add_u32_e32 v109, 0, v6
	v_bfe_u32 v6, v82, 1, 1
	v_bitop3_b32 v3, v5, v3, 1 bitop3:0x78
	v_sub_u32_e32 v2, v2, v4
	s_lshl_b32 s7, s89, 6
	s_lshl_b32 s3, s3, 6
	v_lshlrev_b32_e32 v111, 4, v3
	v_bitop3_b32 v3, v5, v6, 2 bitop3:0x1e
	v_subrev_u32_e32 v2, s7, v2
	s_and_b32 s3, s3, 0xffffff80
	v_lshlrev_b32_e32 v112, 4, v3
	v_bitop3_b32 v3, v5, v6, 4 bitop3:0x1e
	v_subrev_u32_e32 v116, s3, v2
	s_sub_i32 s3, s6, s89
	v_lshlrev_b32_e32 v113, 4, v3
	v_bitop3_b32 v3, v5, v6, 6 bitop3:0x1e
	s_sub_i32 s2, s3, s2
	v_mov_b32_e32 v14, 0
	v_lshlrev_b32_e32 v114, 4, v3
	s_add_i32 s93, s2, 0x7e
	s_add_i32 s94, s7, 0x80
	v_mov_b32_e32 v118, 0xff800000
	v_mov_b32_e32 v117, 0xff800000
	v_mov_b32_e32 v15, v14
	v_mov_b32_e32 v16, v14
	v_mov_b32_e32 v17, v14
	v_mov_b32_e32 v10, v14
	v_mov_b32_e32 v11, v14
	v_mov_b32_e32 v12, v14
	v_mov_b32_e32 v13, v14
	v_mov_b32_e32 v6, v14
	v_mov_b32_e32 v7, v14
	v_mov_b32_e32 v8, v14
	v_mov_b32_e32 v9, v14
	v_mov_b32_e32 v2, v14
	v_mov_b32_e32 v3, v14
	v_mov_b32_e32 v4, v14
	v_mov_b32_e32 v5, v14
	v_mov_b32_e32 v46, v14
	v_mov_b32_e32 v47, v14
	v_mov_b32_e32 v48, v14
	v_mov_b32_e32 v49, v14
	v_mov_b32_e32 v38, v14
	v_mov_b32_e32 v39, v14
	v_mov_b32_e32 v40, v14
	v_mov_b32_e32 v41, v14
	v_mov_b32_e32 v42, v14
	v_mov_b32_e32 v43, v14
	v_mov_b32_e32 v44, v14
	v_mov_b32_e32 v45, v14
	v_mov_b32_e32 v34, v14
	v_mov_b32_e32 v35, v14
	v_mov_b32_e32 v36, v14
	v_mov_b32_e32 v37, v14
	v_mov_b32_e32 v86, v14
	v_mov_b32_e32 v87, v14
	s_branch .LBB0_400

; DI float xmax16(float v) { const unsigned x = __float_as_uint(v); auto r = __builtin_amdgcn_permlane16_swap(x, x, false, false); return fmaxf(__uint_as_float(r[0]), __uint_as_float(r[1])); }
; DI float xmax32(float v) { const unsigned x = __float_as_uint(v); auto r = __builtin_amdgcn_permlane32_swap(x, x, false, false); return fmaxf(__uint_as_float(r[0]), __uint_as_float(r[1])); }
; DI void attn_softmax(f32x4 (&sc)[4], const float* tab, QG& G, int qpos, int dlt, int g, bf16x8 (&pf)[2]) {
;     const float C2 = 0.125f * LOG2E;
;     float mx = -INFINITY;
;     if (dlt >= 3) {
;         const float bc = tab[256];
; #pragma unroll
;         for (int kt = 0; kt < 4; ++kt)
; #pragma unroll
;             for (int e = 0; e < 4; ++e) { const float s = sc[kt][e] * C2 + bc; sc[kt][e] = s; mx = fmaxf(mx, s); }
;     ...
;     mx = xmax16(mx); mx = xmax32(mx);
.LBB0_409:
	s_andn2_b64 vcc, exec, s[30:31]
	s_cbranch_vccnz .LBB0_411
	v_mov_b32_e32 v92, v207
	v_pk_fma_f32 v[100:101], v[66:67], s[10:11], v[92:93] op_sel_hi:[1,0,0]
	v_pk_fma_f32 v[96:97], v[68:69], s[10:11], v[92:93] op_sel_hi:[1,0,0]
	v_max3_f32 v66, v100, s65, v101
	v_pk_fma_f32 v[90:91], v[74:75], s[10:11], v[92:93] op_sel_hi:[1,0,0]
	v_max3_f32 v66, v66, v96, v97
	v_pk_fma_f32 v[88:89], v[76:77], s[10:11], v[92:93] op_sel_hi:[1,0,0]
	v_max3_f32 v66, v66, v90, v91
	v_pk_fma_f32 v[102:103], v[70:71], s[10:11], v[92:93] op_sel_hi:[1,0,0]
	v_max3_f32 v66, v66, v88, v89
	v_max3_f32 v66, v66, v102, v103
	v_pk_fma_f32 v[98:99], v[72:73], s[10:11], v[92:93] op_sel_hi:[1,0,0]
	v_pk_fma_f32 v[94:95], v[78:79], s[10:11], v[92:93] op_sel_hi:[1,0,0]
	v_max3_f32 v66, v66, v98, v99
	v_max3_f32 v66, v66, v94, v95
	v_pk_fma_f32 v[92:93], v[80:81], s[10:11], v[92:93] op_sel_hi:[1,0,0]
	s_nop 0
	v_max3_f32 v105, v66, v92, v93

; DI float xmax16(float v) { const unsigned x = __float_as_uint(v); auto r = __builtin_amdgcn_permlane16_swap(x, x, false, false); return fmaxf(__uint_as_float(r[0]), __uint_as_float(r[1])); }
; DI float xmax32(float v) { const unsigned x = __float_as_uint(v); auto r = __builtin_amdgcn_permlane32_swap(x, x, false, false); return fmaxf(__uint_as_float(r[0]), __uint_as_float(r[1])); }
; DI void attn_softmax(f32x4 (&sc)[4], const float* tab, QG& G, int qpos, int dlt, int g, bf16x8 (&pf)[2]) {
;     const float C2 = 0.125f * LOG2E;
;     float mx = -INFINITY;
;     if (dlt >= 3) {
;         const float bc = tab[256];
; #pragma unroll
;         for (int kt = 0; kt < 4; ++kt)
; #pragma unroll
;             for (int e = 0; e < 4; ++e) { const float s = sc[kt][e] * C2 + bc; sc[kt][e] = s; mx = fmaxf(mx, s); }
;     ...
;     mx = xmax16(mx); mx = xmax32(mx);
.LBB0_413:
	s_andn2_b64 vcc, exec, s[28:29]
	s_cbranch_vccnz .LBB0_398
	v_mov_b32_e32 v66, v207
	v_pk_fma_f32 v[74:75], v[50:51], s[10:11], v[66:67] op_sel_hi:[1,0,0]
	v_pk_fma_f32 v[72:73], v[52:53], s[10:11], v[66:67] op_sel_hi:[1,0,0]
	v_max3_f32 v50, v74, s65, v75
	v_pk_fma_f32 v[70:71], v[58:59], s[10:11], v[66:67] op_sel_hi:[1,0,0]
	v_max3_f32 v50, v50, v72, v73
	v_pk_fma_f32 v[68:69], v[60:61], s[10:11], v[66:67] op_sel_hi:[1,0,0]
	v_max3_f32 v50, v50, v70, v71
	v_pk_fma_f32 v[104:105], v[54:55], s[10:11], v[66:67] op_sel_hi:[1,0,0]
	v_max3_f32 v50, v50, v68, v69
	v_max3_f32 v50, v50, v104, v105
	v_pk_fma_f32 v[80:81], v[56:57], s[10:11], v[66:67] op_sel_hi:[1,0,0]
	v_pk_fma_f32 v[78:79], v[62:63], s[10:11], v[66:67] op_sel_hi:[1,0,0]
	v_max3_f32 v50, v50, v80, v81
	v_max3_f32 v50, v50, v78, v79
	v_pk_fma_f32 v[76:77], v[64:65], s[10:11], v[66:67] op_sel_hi:[1,0,0]
	s_nop 0
	v_max3_f32 v66, v50, v76, v77
	s_branch .LBB0_398

; #define PINM do { asm volatile("" ::: "memory"); __builtin_amdgcn_sched_barrier(0); } while (0)
; DI void scan_item(const Params& p, int item, int lane) {
;     const int i16 = lane & 15, g = lane >> 4;
;     const u16* GT = (const u16*)(p.ws + W_GT); const u16* HH = (const u16*)(p.ws + W_HH); u16* SST = (u16*)(p.ws + W_SST);
;     f32x4 acc[4];
;     if (item < 64) {
;         const int bh = item >> 2, iq = item & 3, u0 = bh * 128, irow = 16 * iq + i16;
; #pragma unroll
;         for (int mt = 0; mt < 4; ++mt) acc[mt] = (f32x4){0.f, 0.f, 0.f, 0.f};
;         ScanSlot s0, s1, s2, s3, s4;
;         scan_load(s0, GT, HH, u0, irow, i16, g); scan_load(s1, GT, HH, u0 + 1, irow, i16, g); scan_load(s2, GT, HH, u0 + 2, irow, i16, g); scan_load(s3, GT, HH, u0 + 3, irow, i16, g);
;         scan_load(s4, GT, HH, u0 + 4, irow, i16, g);
;         const int ul = u0 + 127;
;     ...
;         for (int st = 0; st < 125; st += 5) {
;             const int u = u0 + st;
;             scan_step(s0, acc, SST + (size_t)u * 4096, irow, g);       PINM; scan_load(s0, GT, HH, min(u + 5, ul), irow, i16, g); PINM;
;             scan_step(s1, acc, SST + (size_t)(u + 1) * 4096, irow, g); PINM; scan_load(s1, GT, HH, min(u + 6, ul), irow, i16, g); PINM;
;             scan_step(s2, acc, SST + (size_t)(u + 2) * 4096, irow, g); PINM; scan_load(s2, GT, HH, min(u + 7, ul), irow, i16, g); PINM;
;             scan_step(s3, acc, SST + (size_t)(u + 3) * 4096, irow, g); PINM; scan_load(s3, GT, HH, min(u + 8, ul), irow, i16, g); PINM;
;             scan_step(s4, acc, SST + (size_t)(u + 4) * 4096, irow, g); PINM; scan_load(s4, GT, HH, min(u + 9, ul), irow, i16, g); PINM;
;         }
; DI void phase_scan_attn(const Params& p, char* lds) {
;     ...
;     if (blockIdx.x < 64) {
;         if (wave == 0) { const int x_ = blockIdx.x & 7, k_ = blockIdx.x >> 3;
;             scan_item(p, (x_ + 8 * (k_ >> 2)) * 4 + (k_ & 3), lane); }
.LBB0_435:
	s_and_b64 vcc, exec, s[0:1]
	v_readlane_b32 s64, v236, 7
	s_cbranch_vccz .LBB0_440
	s_cmp_gt_u32 s11, 63
	s_cbranch_scc1 .Lscan_helper
	v_mov_b32_e32 v241, 0
	v_mov_b32_e32 v240, 0
	ds_write_b32 v241, v240
	s_waitcnt lgkmcnt(0)
	s_barrier
	v_readlane_b32 s0, v236, 4
	s_and_b32 s0, s0, 28
	s_and_b32 s1, s33, 32
	s_or_b32 s2, s0, s1
	s_add_u32 s4, s54, 0xb414800
	s_addc_u32 s5, s55, 0
	s_add_u32 s6, s54, 0xc614800
	s_addc_u32 s7, s55, 0
	s_lshl_b32 s0, s33, 1
	s_lshl_b32 s8, s2, 5
	s_lshl_b32 s3, s2, 18
	v_and_or_b32 v206, s0, 48, v223
	s_add_u32 s0, s4, s3
	s_addc_u32 s1, s5, 0
	v_mov_b32_e32 v221, 0
	v_lshl_add_u64 v[2:3], s[0:1], 0, v[220:221]
	v_lshlrev_b32_e32 v202, 7, v223
	v_mov_b32_e32 v203, v221
	v_lshl_add_u64 v[2:3], v[2:3], 0, v[202:203]
	s_movk_i32 s9, 0x1000
	global_load_dwordx4 v[106:109], v[2:3], off
	global_load_dwordx4 v[102:105], v[2:3], off offset:64
	global_load_dwordx4 v[90:93], v[2:3], off offset:2048
	global_load_dwordx4 v[86:89], v[2:3], off offset:2112
	v_add_co_u32_e32 v2, vcc, s9, v2
	s_add_u32 s0, s6, s3
	s_nop 0
	v_addc_co_u32_e32 v3, vcc, 0, v3, vcc
	s_addc_u32 s1, s7, 0
	v_lshlrev_b32_e32 v204, 7, v206
	v_mov_b32_e32 v205, v221
	s_or_b32 s10, s3, 0x2000
	global_load_dwordx4 v[82:85], v[2:3], off
	global_load_dwordx4 v[78:81], v[2:3], off offset:64
	global_load_dwordx4 v[62:65], v[2:3], off offset:2048
	global_load_dwordx4 v[50:53], v[2:3], off offset:2112
	v_lshl_add_u64 v[2:3], s[0:1], 0, v[204:205]
	s_add_u32 s0, s4, s10
	v_lshl_add_u64 v[2:3], v[2:3], 0, v[220:221]
	s_addc_u32 s1, s5, 0
	global_load_dwordx4 v[110:113], v[2:3], off
	global_load_dwordx4 v[98:101], v[2:3], off offset:64
	v_lshl_add_u64 v[2:3], s[0:1], 0, v[220:221]
	v_lshl_add_u64 v[2:3], v[2:3], 0, v[202:203]
	global_load_dwordx4 v[74:77], v[2:3], off
	global_load_dwordx4 v[70:73], v[2:3], off offset:64
	global_load_dwordx4 v[54:57], v[2:3], off offset:2048
	global_load_dwordx4 v[58:61], v[2:3], off offset:2112
	v_add_co_u32_e32 v2, vcc, s9, v2
	s_add_u32 s0, s6, s10
	s_nop 0
	v_addc_co_u32_e32 v3, vcc, 0, v3, vcc
	s_addc_u32 s1, s7, 0
	s_or_b32 s10, s3, 0x4000
	global_load_dwordx4 v[46:49], v[2:3], off
	global_load_dwordx4 v[42:45], v[2:3], off offset:64
	global_load_dwordx4 v[30:33], v[2:3], off offset:2048
	global_load_dwordx4 v[26:29], v[2:3], off offset:2112
	v_lshl_add_u64 v[2:3], s[0:1], 0, v[204:205]
	s_add_u32 s0, s4, s10
	v_lshl_add_u64 v[2:3], v[2:3], 0, v[220:221]
	s_addc_u32 s1, s5, 0
	global_load_dwordx4 v[94:97], v[2:3], off
	global_load_dwordx4 v[66:69], v[2:3], off offset:64
	v_lshl_add_u64 v[2:3], s[0:1], 0, v[220:221]
	v_lshl_add_u64 v[2:3], v[2:3], 0, v[202:203]
	v_add_co_u32_e32 v114, vcc, s9, v2
	s_add_u32 s0, s6, s10
	s_nop 0
	v_addc_co_u32_e32 v115, vcc, 0, v3, vcc
	s_addc_u32 s1, s7, 0
	s_or_b32 s10, s3, 0x6000
	global_load_dwordx4 v[38:41], v[2:3], off
	global_load_dwordx4 v[34:37], v[2:3], off offset:64
	global_load_dwordx4 v[22:25], v[2:3], off offset:2048
	global_load_dwordx4 v[18:21], v[2:3], off offset:2112
	global_load_dwordx4 v[14:17], v[114:115], off
	global_load_dwordx4 v[10:13], v[114:115], off offset:64
	global_load_dwordx4 v[6:9], v[114:115], off offset:2048
	s_nop 0
	global_load_dwordx4 v[2:5], v[114:115], off offset:2112
	v_lshl_add_u64 v[114:115], s[0:1], 0, v[204:205]
	s_add_u32 s0, s4, s10
	s_addc_u32 s1, s5, 0
	v_lshl_add_u64 v[116:117], s[0:1], 0, v[220:221]
	s_add_u32 s0, s6, s10
	s_addc_u32 s1, s7, 0
	s_or_b32 s10, s3, 0x8000
	v_lshl_add_u64 v[122:123], v[116:117], 0, v[202:203]
	v_lshl_add_u64 v[116:117], s[0:1], 0, v[204:205]
	s_add_u32 s0, s4, s10
	s_addc_u32 s1, s5, 0
	v_add_co_u32_e32 v124, vcc, s9, v122
	v_lshl_add_u64 v[134:135], v[116:117], 0, v[220:221]
	v_lshl_add_u64 v[116:117], s[0:1], 0, v[220:221]
	s_add_u32 s0, s6, s10
	v_addc_co_u32_e32 v125, vcc, 0, v123, vcc
	v_lshl_add_u64 v[136:137], v[116:117], 0, v[202:203]
	s_addc_u32 s1, s7, 0
	v_add_co_u32_e32 v186, vcc, s9, v136
	v_lshl_add_u64 v[116:117], s[0:1], 0, v[204:205]
	v_lshl_add_u64 v[114:115], v[114:115], 0, v[220:221]
	v_addc_co_u32_e32 v187, vcc, 0, v137, vcc
	v_lshl_add_u64 v[188:189], v[116:117], 0, v[220:221]
	global_load_dwordx4 v[118:121], v[114:115], off
	s_nop 0
	global_load_dwordx4 v[114:117], v[114:115], off offset:64
	s_nop 0
	global_load_dwordx4 v[178:181], v[122:123], off
	global_load_dwordx4 v[162:165], v[122:123], off offset:64
	global_load_dwordx4 v[146:149], v[122:123], off offset:2048
	global_load_dwordx4 v[150:153], v[122:123], off offset:2112
	global_load_dwordx4 v[130:133], v[124:125], off
	global_load_dwordx4 v[138:141], v[124:125], off offset:64
	global_load_dwordx4 v[126:129], v[124:125], off offset:2048
	s_nop 0
	global_load_dwordx4 v[122:125], v[124:125], off offset:2112
	s_nop 0
	global_load_dwordx4 v[194:197], v[134:135], off
	global_load_dwordx4 v[166:169], v[134:135], off offset:64
	global_load_dwordx4 v[190:193], v[136:137], off
	global_load_dwordx4 v[182:185], v[136:137], off offset:64
	global_load_dwordx4 v[170:173], v[136:137], off offset:2048
	global_load_dwordx4 v[174:177], v[136:137], off offset:2112
	global_load_dwordx4 v[154:157], v[186:187], off
	global_load_dwordx4 v[158:161], v[186:187], off offset:64
	global_load_dwordx4 v[142:145], v[186:187], off offset:2048
	s_nop 0
	global_load_dwordx4 v[134:137], v[186:187], off offset:2112
	global_load_dwordx4 v[198:201], v[188:189], off
	s_nop 0
	global_load_dwordx4 v[186:189], v[188:189], off offset:64
	v_lshlrev_b32_e32 v222, 6, v206
	v_lshl_add_u64 v[206:207], s[4:5], 0, v[220:221]
	v_lshl_add_u64 v[226:227], v[206:207], 0, v[202:203]
	v_lshl_add_u64 v[202:203], s[6:7], 0, v[204:205]
	v_lshl_add_u64 v[228:229], v[202:203], 0, v[220:221]
	v_and_b32_e32 v202, 48, v0
	v_or3_b32 v202, s3, v202, v204
	v_mov_b32_e32 v203, v221
	v_lshrrev_b32_e32 v225, 4, v218
	v_lshl_add_u64 v[202:203], s[54:55], 0, v[202:203]
	s_mov_b64 s[4:5], 0xea1c840
	s_mov_b32 s1, 0
	s_or_b32 s10, s8, 0x7f
	v_lshl_add_u64 v[230:231], v[202:203], 0, s[4:5]
	s_mov_b32 s6, -5
	s_movk_i32 s7, 0x8000
	s_movk_i32 s11, 0xa000
	s_movk_i32 s12, 0xc000
	s_movk_i32 s13, 0xe000
	s_mov_b64 s[4:5], 0xa000
	v_mov_b32_e32 v206, v221
	v_mov_b32_e32 v207, v221
	v_mov_b32_e32 v208, v221
	v_mov_b32_e32 v209, v221
	v_mov_b32_e32 v214, v221
	v_mov_b32_e32 v215, v221
	v_mov_b32_e32 v216, v221
	v_mov_b32_e32 v217, v221
	v_mov_b32_e32 v202, v221
	v_mov_b32_e32 v203, v221
	v_mov_b32_e32 v204, v221
	v_mov_b32_e32 v210, v221
	v_mov_b32_e32 v211, v221
	v_mov_b32_e32 v212, v221
	v_mov_b32_e32 v213, v221
	v_lshlrev_b32_e32 v224, 3, v225
.LBB0_438:
	s_add_i32 s32, s6, 5
	v_mov_b32_e32 v240, s32
	ds_write_b32 v241, v240
	v_cvt_pk_bf16_f32 v206, v206, v207
	v_cvt_pk_bf16_f32 v207, v208, v209
	v_cvt_pk_bf16_f32 v208, v214, v215
	v_cvt_pk_bf16_f32 v209, v216, v217
	s_cmp_lg_u32 s6, -5
	s_cbranch_scc1 .Lscan_w0
	s_waitcnt vmcnt(40)

; DI unsigned pack2(float lo, float hi) { f32x2_t v = {lo, hi}; bf16x2_t b = __builtin_convertvector(v, bf16x2_t); return __builtin_bit_cast(unsigned, b); }
; DI float bflo(unsigned u) { return __uint_as_float(u << 16); }
; DI float bfhi(unsigned u) { return __uint_as_float(u & 0xffff0000u); }
; #define PINM do { asm volatile("" ::: "memory"); __builtin_amdgcn_sched_barrier(0); } while (0)
; DI void scan_step(const ScanSlot& s, f32x4 (&acc)[4], u16* sst, int irow, int g) {
;     unsigned pk[4][2];
; #pragma unroll
;     for (int mt = 0; mt < 4; ++mt) { pk[mt][0] = pack2(acc[mt][0], acc[mt][1]); pk[mt][1] = pack2(acc[mt][2], acc[mt][3]); }
;     bf16x8 bfr[2];
; #pragma unroll
;     for (int ks = 0; ks < 2; ++ks) { uint4 w = {pk[2 * ks][0], pk[2 * ks][1], pk[2 * ks + 1][0], pk[2 * ks + 1][1]}; bfr[ks] = __builtin_bit_cast(bf16x8, w);
;         { typedef unsigned u32x4_ __attribute__((ext_vector_type(4))); const u32x4_ wv_ = {w.x, w.y, w.z, w.w}; __builtin_nontemporal_store(wv_, (u32x4_*)(sst + irow * 64 + 32 * ks + 8 * g)); } }
; #pragma unroll
;     for (int mt = 0; mt < 4; ++mt) {
;         const unsigned hx = (mt & 1) ? s.gh[mt >> 1].z : s.gh[mt >> 1].x, hy = (mt & 1) ? s.gh[mt >> 1].w : s.gh[mt >> 1].y;
;         f32x4 c = {bflo(hx), bfhi(hx), bflo(hy), bfhi(hy)};
; #pragma unroll
;         for (int ks = 0; ks < 2; ++ks) c = __builtin_amdgcn_mfma_f32_16x16x32_bf16(__builtin_bit_cast(bf16x8, s.ga[mt][ks]), bfr[ks], c, 0, 0, 0);
;         acc[mt] = c;
;     }
; }
; DI void scan_item(const Params& p, int item, int lane) {
;     ...
;             scan_step(s0, acc, SST + (size_t)u * 4096, irow, g);       PINM; scan_load(s0, GT, HH, min(u + 5, ul), irow, i16, g); PINM;
;             scan_step(s1, acc, SST + (size_t)(u + 1) * 4096, irow, g); PINM; scan_load(s1, GT, HH, min(u + 6, ul), irow, i16, g); PINM;
;             scan_step(s2, acc, SST + (size_t)(u + 2) * 4096, irow, g); PINM; scan_load(s2, GT, HH, min(u + 7, ul), irow, i16, g); PINM;
;             scan_step(s3, acc, SST + (size_t)(u + 3) * 4096, irow, g); PINM; scan_load(s3, GT, HH, min(u + 8, ul), irow, i16, g); PINM;
;             scan_step(s4, acc, SST + (size_t)(u + 4) * 4096, irow, g); PINM; scan_load(s4, GT, HH, min(u + 9, ul), irow, i16, g); PINM;
.Lscan_w3:
	s_waitcnt vmcnt(48)
	v_cvt_pk_bf16_f32 v206, v206, v207
	v_cvt_pk_bf16_f32 v207, v208, v209
	v_cvt_pk_bf16_f32 v208, v214, v215
	v_cvt_pk_bf16_f32 v209, v216, v217
	v_lshlrev_b32_e32 v212, 16, v194
	v_and_b32_e32 v213, 0xffff0000, v194
	v_lshlrev_b32_e32 v214, 16, v195
	v_and_b32_e32 v215, 0xffff0000, v195
	v_cvt_pk_bf16_f32 v210, v232, v233
	v_cvt_pk_bf16_f32 v211, v234, v235
	v_mfma_f32_16x16x32_bf16 v[178:181], v[178:181], v[206:209], v[212:215]
	s_nop 2
	v_cvt_pk_bf16_f32 v212, v202, v203
	v_cvt_pk_bf16_f32 v213, v204, v205
	s_nop 1
	v_mfma_f32_16x16x32_bf16 v[202:205], v[162:165], v[210:213], v[178:181]
	v_lshlrev_b32_e32 v162, 16, v196
	v_and_b32_e32 v163, 0xffff0000, v196
	v_lshlrev_b32_e32 v164, 16, v197
	v_and_b32_e32 v165, 0xffff0000, v197
	s_nop 1
	v_mfma_f32_16x16x32_bf16 v[146:149], v[146:149], v[206:209], v[162:165]
	v_mfma_f32_16x16x32_bf16 v[214:217], v[150:153], v[210:213], v[146:149]
	s_nop 6
	v_lshlrev_b32_e32 v146, 16, v166
	v_and_b32_e32 v147, 0xffff0000, v166
	v_lshlrev_b32_e32 v148, 16, v167
	v_and_b32_e32 v149, 0xffff0000, v167
	s_nop 1
	v_mfma_f32_16x16x32_bf16 v[130:133], v[130:133], v[206:209], v[146:149]
	v_mfma_f32_16x16x32_bf16 v[232:235], v[138:141], v[210:213], v[130:133]
	s_nop 6
	v_lshlrev_b32_e32 v130, 16, v168
	v_and_b32_e32 v131, 0xffff0000, v168
	v_lshlrev_b32_e32 v132, 16, v169
	v_and_b32_e32 v133, 0xffff0000, v169
	s_nop 1
	v_mfma_f32_16x16x32_bf16 v[126:129], v[126:129], v[206:209], v[130:133]
	s_nop 2
	v_add_co_u32_e32 v130, vcc, s13, v230
	s_nop 1
	v_addc_co_u32_e32 v131, vcc, -1, v231, vcc
	global_store_dwordx4 v[130:131], v[206:209], off offset:-64 nt
	global_store_dwordx4 v[130:131], v[210:213], off nt
	s_nop 0
	v_mfma_f32_16x16x32_bf16 v[206:209], v[122:125], v[210:213], v[126:129]
	s_add_i32 s0, s14, 13
	s_min_u32 s0, s0, s10
	s_lshl_b32 s0, s0, 13
	v_lshl_add_u64 v[122:123], v[226:227], 0, s[0:1]
	global_load_dwordx4 v[178:181], v[122:123], off
	global_load_dwordx4 v[162:165], v[122:123], off offset:64
	global_load_dwordx4 v[146:149], v[122:123], off offset:2048
	global_load_dwordx4 v[150:153], v[122:123], off offset:2112
	v_add_co_u32_e32 v122, vcc, s9, v122
	v_lshl_add_u64 v[166:167], v[228:229], 0, s[0:1]
	s_nop 0
	v_addc_co_u32_e32 v123, vcc, 0, v123, vcc
	global_load_dwordx4 v[130:133], v[122:123], off
	global_load_dwordx4 v[138:141], v[122:123], off offset:64
	global_load_dwordx4 v[126:129], v[122:123], off offset:2048
	s_nop 0
	global_load_dwordx4 v[122:125], v[122:123], off offset:2112
	s_nop 0
	global_load_dwordx4 v[194:197], v[166:167], off
	s_nop 0
	global_load_dwordx4 v[166:169], v[166:167], off offset:64
	s_waitcnt vmcnt(48)
	v_cvt_pk_bf16_f32 v210, v202, v203
	v_cvt_pk_bf16_f32 v211, v204, v205
	v_cvt_pk_bf16_f32 v212, v214, v215
	v_cvt_pk_bf16_f32 v213, v216, v217
	v_lshlrev_b32_e32 v202, 16, v198
	v_and_b32_e32 v203, 0xffff0000, v198
	v_lshlrev_b32_e32 v204, 16, v199
	v_and_b32_e32 v205, 0xffff0000, v199
	v_cvt_pk_bf16_f32 v232, v232, v233
	v_cvt_pk_bf16_f32 v233, v234, v235
	v_mfma_f32_16x16x32_bf16 v[190:193], v[190:193], v[210:213], v[202:205]
	v_cvt_pk_bf16_f32 v234, v206, v207
	v_cvt_pk_bf16_f32 v235, v208, v209
	global_store_dwordx4 v[230:231], v[210:213], off offset:-64 nt
	global_store_dwordx4 v[230:231], v[232:235], off nt
	v_mfma_f32_16x16x32_bf16 v[206:209], v[182:185], v[232:235], v[190:193]
	v_lshlrev_b32_e32 v182, 16, v200
	v_and_b32_e32 v183, 0xffff0000, v200
	v_lshlrev_b32_e32 v184, 16, v201
	v_and_b32_e32 v185, 0xffff0000, v201
	s_nop 1
	v_mfma_f32_16x16x32_bf16 v[170:173], v[170:173], v[210:213], v[182:185]
	v_mfma_f32_16x16x32_bf16 v[214:217], v[174:177], v[232:235], v[170:173]
	s_nop 6
	v_lshlrev_b32_e32 v170, 16, v186
	v_and_b32_e32 v171, 0xffff0000, v186
	v_lshlrev_b32_e32 v172, 16, v187
	v_and_b32_e32 v173, 0xffff0000, v187
	s_nop 1
	v_mfma_f32_16x16x32_bf16 v[154:157], v[154:157], v[210:213], v[170:173]
	v_mfma_f32_16x16x32_bf16 v[202:205], v[158:161], v[232:235], v[154:157]
	s_nop 6
	v_lshlrev_b32_e32 v154, 16, v188
	v_and_b32_e32 v155, 0xffff0000, v188
	v_lshlrev_b32_e32 v156, 16, v189
	v_and_b32_e32 v157, 0xffff0000, v189
	s_nop 1
	v_mfma_f32_16x16x32_bf16 v[142:145], v[142:145], v[210:213], v[154:157]
	v_mfma_f32_16x16x32_bf16 v[210:213], v[134:137], v[232:235], v[142:145]
	s_add_i32 s14, s14, 14
	s_min_u32 s0, s14, s10
	s_lshl_b32 s0, s0, 13
	v_lshl_add_u64 v[134:135], v[226:227], 0, s[0:1]
	global_load_dwordx4 v[190:193], v[134:135], off
	global_load_dwordx4 v[182:185], v[134:135], off offset:64
	global_load_dwordx4 v[170:173], v[134:135], off offset:2048
	global_load_dwordx4 v[174:177], v[134:135], off offset:2112
	v_add_co_u32_e32 v134, vcc, s9, v134
	v_lshl_add_u64 v[186:187], v[228:229], 0, s[0:1]
	s_nop 0
	v_addc_co_u32_e32 v135, vcc, 0, v135, vcc
	global_load_dwordx4 v[154:157], v[134:135], off
	global_load_dwordx4 v[158:161], v[134:135], off offset:64
	global_load_dwordx4 v[142:145], v[134:135], off offset:2048
	s_nop 0
	global_load_dwordx4 v[134:137], v[134:135], off offset:2112
	s_nop 0
	global_load_dwordx4 v[198:201], v[186:187], off
	s_nop 0
	global_load_dwordx4 v[186:189], v[186:187], off offset:64
	s_add_i32 s6, s6, 5
	s_cmpk_gt_u32 s6, 0x77
	v_lshl_add_u64 v[230:231], v[230:231], 0, s[4:5]
	s_cbranch_scc0 .LBB0_438
; DI unsigned pack2(float lo, float hi) { f32x2_t v = {lo, hi}; bf16x2_t b = __builtin_convertvector(v, bf16x2_t); return __builtin_bit_cast(unsigned, b); }
; DI float bflo(unsigned u) { return __uint_as_float(u << 16); }
; DI float bfhi(unsigned u) { return __uint_as_float(u & 0xffff0000u); }
; #define PINM do { asm volatile("" ::: "memory"); __builtin_amdgcn_sched_barrier(0); } while (0)
; DI void scan_step(const ScanSlot& s, f32x4 (&acc)[4], u16* sst, int irow, int g) {
;     unsigned pk[4][2];
; #pragma unroll
;     for (int mt = 0; mt < 4; ++mt) { pk[mt][0] = pack2(acc[mt][0], acc[mt][1]); pk[mt][1] = pack2(acc[mt][2], acc[mt][3]); }
;     bf16x8 bfr[2];
; #pragma unroll
;     for (int ks = 0; ks < 2; ++ks) { uint4 w = {pk[2 * ks][0], pk[2 * ks][1], pk[2 * ks + 1][0], pk[2 * ks + 1][1]}; bfr[ks] = __builtin_bit_cast(bf16x8, w);
;         { typedef unsigned u32x4_ __attribute__((ext_vector_type(4))); const u32x4_ wv_ = {w.x, w.y, w.z, w.w}; __builtin_nontemporal_store(wv_, (u32x4_*)(sst + irow * 64 + 32 * ks + 8 * g)); } }
; #pragma unroll
;     for (int mt = 0; mt < 4; ++mt) {
;         const unsigned hx = (mt & 1) ? s.gh[mt >> 1].z : s.gh[mt >> 1].x, hy = (mt & 1) ? s.gh[mt >> 1].w : s.gh[mt >> 1].y;
;         f32x4 c = {bflo(hx), bfhi(hx), bflo(hy), bfhi(hy)};
; #pragma unroll
;         for (int ks = 0; ks < 2; ++ks) c = __builtin_amdgcn_mfma_f32_16x16x32_bf16(__builtin_bit_cast(bf16x8, s.ga[mt][ks]), bfr[ks], c, 0, 0, 0);
;         acc[mt] = c;
;     }
; }
; DI void scan_item(const Params& p, int item, int lane) {
;     ...
;         scan_step(s0, acc, SST + (size_t)(u0 + 125) * 4096, irow, g); PINM;
;         scan_step(s1, acc, SST + (size_t)(u0 + 126) * 4096, irow, g); PINM;
;         scan_step(s2, acc, SST + (size_t)(u0 + 127) * 4096, irow, g);
;     ...
;         float* fout = p.out + O_SP + (size_t)bh * 4096;
; #pragma unroll
;         for (int mt = 0; mt < 4; ++mt) *(f32x4*)(fout + irow * 64 + 16 * mt + 4 * g) = acc[mt];
	s_waitcnt vmcnt(0)
	v_cvt_pk_bf16_f32 v122, v206, v207
	v_cvt_pk_bf16_f32 v123, v208, v209
	v_cvt_pk_bf16_f32 v124, v214, v215
	v_cvt_pk_bf16_f32 v125, v216, v217
	v_lshlrev_b32_e32 v130, 16, v110
	v_and_b32_e32 v131, 0xffff0000, v110
	v_lshlrev_b32_e32 v132, 16, v111
	v_and_b32_e32 v133, 0xffff0000, v111
	v_cvt_pk_bf16_f32 v126, v202, v203
	v_cvt_pk_bf16_f32 v127, v204, v205
	v_mfma_f32_16x16x32_bf16 v[106:109], v[106:109], v[122:125], v[130:133]
	v_cvt_pk_bf16_f32 v128, v210, v211
	v_cvt_pk_bf16_f32 v129, v212, v213
	s_add_u32 s0, s54, 0xea14800
	s_addc_u32 s1, s55, 0
	v_mfma_f32_16x16x32_bf16 v[102:105], v[102:105], v[126:129], v[106:109]
	s_add_u32 s4, s0, s3
	s_addc_u32 s5, s1, 0
	v_lshlrev_b32_e32 v110, 1, v222
	v_lshlrev_b32_e32 v106, 16, v112
	v_and_b32_e32 v107, 0xffff0000, v112
	v_lshlrev_b32_e32 v108, 16, v113
	v_and_b32_e32 v109, 0xffff0000, v113
	v_mov_b32_e32 v111, 0
	v_lshlrev_b32_e32 v130, 1, v224
	v_mfma_f32_16x16x32_bf16 v[90:93], v[90:93], v[122:125], v[106:109]
	v_mov_b32_e32 v131, v111
	s_mov_b32 s3, 0xfa000
	v_mfma_f32_16x16x32_bf16 v[86:89], v[86:89], v[126:129], v[90:93]
	v_lshl_add_u64 v[106:107], s[4:5], 0, v[110:111]
	v_lshl_add_u64 v[106:107], v[106:107], 0, v[130:131]
	s_mov_b64 s[4:5], 0xfa000
	s_nop 1
	v_lshlrev_b32_e32 v90, 16, v98
	v_and_b32_e32 v91, 0xffff0000, v98
	v_lshlrev_b32_e32 v92, 16, v99
	v_and_b32_e32 v93, 0xffff0000, v99
	s_nop 1
	v_mfma_f32_16x16x32_bf16 v[82:85], v[82:85], v[122:125], v[90:93]
	v_mfma_f32_16x16x32_bf16 v[78:81], v[78:81], v[126:129], v[82:85]
	s_nop 1
	v_lshl_add_u64 v[90:91], v[106:107], 0, s[4:5]
	s_nop 3
	v_lshlrev_b32_e32 v82, 16, v100
	v_and_b32_e32 v83, 0xffff0000, v100
	v_lshlrev_b32_e32 v84, 16, v101
	v_and_b32_e32 v85, 0xffff0000, v101
	s_nop 1
	v_mfma_f32_16x16x32_bf16 v[62:65], v[62:65], v[122:125], v[82:85]
	s_nop 2
	v_add_co_u32_e32 v82, vcc, s3, v106
	v_mfma_f32_16x16x32_bf16 v[50:53], v[50:53], v[126:129], v[62:65]
	s_nop 0
	v_addc_co_u32_e32 v83, vcc, 0, v107, vcc
	global_store_dwordx4 v[82:83], v[122:125], off nt
	global_store_dwordx4 v[90:91], v[126:129], off offset:64 nt
	v_cvt_pk_bf16_f32 v62, v102, v103
	v_cvt_pk_bf16_f32 v63, v104, v105
	v_cvt_pk_bf16_f32 v64, v86, v87
	v_cvt_pk_bf16_f32 v65, v88, v89
	v_lshlrev_b32_e32 v82, 16, v94
	v_and_b32_e32 v83, 0xffff0000, v94
	v_lshlrev_b32_e32 v84, 16, v95
	v_and_b32_e32 v85, 0xffff0000, v95
	v_cvt_pk_bf16_f32 v78, v78, v79
	v_cvt_pk_bf16_f32 v79, v80, v81
	v_mfma_f32_16x16x32_bf16 v[74:77], v[74:77], v[62:65], v[82:85]
	v_cvt_pk_bf16_f32 v80, v50, v51
	v_cvt_pk_bf16_f32 v81, v52, v53
	s_mov_b32 s3, 0xfc000
	s_mov_b64 s[4:5], 0xfc000
	v_mfma_f32_16x16x32_bf16 v[50:53], v[70:73], v[78:81], v[74:77]
	v_lshlrev_b32_e32 v70, 16, v96
	v_and_b32_e32 v71, 0xffff0000, v96
	v_lshlrev_b32_e32 v72, 16, v97
	v_and_b32_e32 v73, 0xffff0000, v97
	s_nop 1
	v_mfma_f32_16x16x32_bf16 v[54:57], v[54:57], v[62:65], v[70:73]
	v_mfma_f32_16x16x32_bf16 v[54:57], v[58:61], v[78:81], v[54:57]
	v_lshlrev_b32_e32 v58, 16, v66
	v_and_b32_e32 v59, 0xffff0000, v66
	v_lshlrev_b32_e32 v60, 16, v67
	v_and_b32_e32 v61, 0xffff0000, v67
	s_nop 1
	v_mfma_f32_16x16x32_bf16 v[46:49], v[46:49], v[62:65], v[58:61]
	v_mfma_f32_16x16x32_bf16 v[42:45], v[42:45], v[78:81], v[46:49]
	s_nop 1
	v_lshl_add_u64 v[58:59], v[106:107], 0, s[4:5]
	s_nop 3
	v_lshlrev_b32_e32 v46, 16, v68
	v_and_b32_e32 v47, 0xffff0000, v68
	v_lshlrev_b32_e32 v48, 16, v69
	v_and_b32_e32 v49, 0xffff0000, v69
	s_nop 1
	v_mfma_f32_16x16x32_bf16 v[30:33], v[30:33], v[62:65], v[46:49]
	s_nop 2
	v_add_co_u32_e32 v46, vcc, s3, v106
	v_mfma_f32_16x16x32_bf16 v[26:29], v[26:29], v[78:81], v[30:33]
	s_nop 0
	v_addc_co_u32_e32 v47, vcc, 0, v107, vcc
	global_store_dwordx4 v[46:47], v[62:65], off nt
	global_store_dwordx4 v[58:59], v[78:81], off offset:64 nt
	v_cvt_pk_bf16_f32 v30, v50, v51
	v_cvt_pk_bf16_f32 v31, v52, v53
	v_cvt_pk_bf16_f32 v32, v54, v55
	v_cvt_pk_bf16_f32 v33, v56, v57
	v_lshlrev_b32_e32 v46, 16, v118
	v_and_b32_e32 v47, 0xffff0000, v118
	v_lshlrev_b32_e32 v48, 16, v119
	v_and_b32_e32 v49, 0xffff0000, v119
	v_cvt_pk_bf16_f32 v42, v42, v43
	v_cvt_pk_bf16_f32 v43, v44, v45
	v_mfma_f32_16x16x32_bf16 v[38:41], v[38:41], v[30:33], v[46:49]
	v_cvt_pk_bf16_f32 v44, v26, v27
	v_cvt_pk_bf16_f32 v45, v28, v29
	s_lshl_b32 s3, s10, 13
	s_add_u32 s0, s0, s3
	v_mfma_f32_16x16x32_bf16 v[26:29], v[34:37], v[42:45], v[38:41]
	v_lshlrev_b32_e32 v34, 16, v120
	v_and_b32_e32 v35, 0xffff0000, v120
	v_lshlrev_b32_e32 v36, 16, v121
	v_and_b32_e32 v37, 0xffff0000, v121
	s_addc_u32 s1, s1, 0
	s_nop 0
	v_mfma_f32_16x16x32_bf16 v[22:25], v[22:25], v[30:33], v[34:37]
	v_mfma_f32_16x16x32_bf16 v[18:21], v[18:21], v[42:45], v[22:25]
	s_nop 6
	v_lshlrev_b32_e32 v22, 16, v114
	v_and_b32_e32 v23, 0xffff0000, v114
	v_lshlrev_b32_e32 v24, 16, v115
	v_and_b32_e32 v25, 0xffff0000, v115
	s_nop 1
	v_mfma_f32_16x16x32_bf16 v[14:17], v[14:17], v[30:33], v[22:25]
	v_mfma_f32_16x16x32_bf16 v[10:13], v[10:13], v[42:45], v[14:17]
	s_nop 1
	v_lshl_add_u64 v[22:23], s[0:1], 0, v[110:111]
	s_lshl_b32 s0, s2, 12
	s_add_u32 s0, s52, s0
	s_nop 1
	v_lshlrev_b32_e32 v14, 16, v116
	v_and_b32_e32 v15, 0xffff0000, v116
	v_lshlrev_b32_e32 v16, 16, v117
	v_and_b32_e32 v17, 0xffff0000, v117
	s_addc_u32 s1, s53, 0
	v_lshlrev_b32_e32 v110, 2, v222
	v_mfma_f32_16x16x32_bf16 v[6:9], v[6:9], v[30:33], v[14:17]
	v_mfma_f32_16x16x32_bf16 v[2:5], v[2:5], v[42:45], v[6:9]
	s_nop 1
	v_lshl_add_u64 v[14:15], v[22:23], 0, v[130:131]
	global_store_dwordx4 v[14:15], v[30:33], off nt
	global_store_dwordx4 v[14:15], v[42:45], off offset:64 nt
	s_nop 1
	v_lshl_add_u64 v[6:7], s[0:1], 0, v[110:111]
	v_lshlrev_b32_e32 v110, 4, v225
	v_lshl_add_u64 v[6:7], v[6:7], 0, v[110:111]
	s_mov_b64 s[0:1], 0x4800000
	v_lshl_add_u64 v[8:9], v[6:7], 0, s[0:1]
	v_add_co_u32_e32 v6, vcc, 0x4800000, v6
	s_nop 1
	v_addc_co_u32_e32 v7, vcc, 0, v7, vcc
	global_store_dwordx4 v[6:7], v[26:29], off
	global_store_dwordx4 v[8:9], v[18:21], off offset:64
	global_store_dwordx4 v[8:9], v[10:13], off offset:128
	global_store_dwordx4 v[8:9], v[2:5], off offset:192
	s_branch .LBB0_440
; DI unsigned xb_add(unsigned* p, unsigned v) { return __hip_atomic_fetch_add(p, v, __ATOMIC_RELAXED, __HIP_MEMORY_SCOPE_AGENT); }
; DI void xcd_barrier(const XcdBarrier& b) {
;     asm volatile("s_waitcnt vmcnt(0)" ::: "memory");
;     __syncthreads();
;     if (threadIdx.x == 0) {
;         unsigned* bar = b.bar;
;         __builtin_amdgcn_s_waitcnt(0);
;         unsigned nloc = b.st[0], nx = b.st[1];
;         if (nloc == 0u) { xcd_barrier_complete(bar, b.x, nloc, nx); b.st[0] = nloc; b.st[1] = nx; }
;         const unsigned old = xb_add(&bar[XB_XSUB(b.x)], 1u);
.Lscan_helper:
	s_barrier
	s_cmp_lg_u32 s11, 64
	s_cbranch_scc1 .LBB0_440
	v_readlane_b32 s96, v236, 4
	s_and_b32 s96, s96, 28
	s_and_b32 s97, s33, 32
	s_or_b32 s96, s96, s97
	s_lshl_b32 s96, s96, 18
	s_add_u32 s98, s54, 0xb414800
	s_addc_u32 s99, s55, 0
	s_add_u32 s98, s98, s96
	s_addc_u32 s99, s99, 0
	s_add_u32 s100, s54, 0xc614800
	s_addc_u32 s101, s55, 0
	s_add_u32 s100, s100, s96
	s_addc_u32 s101, s101, 0
	s_add_u32 s98, s98, 0xa000
	s_addc_u32 s99, s99, 0
	s_add_u32 s100, s100, 0xa000
	s_addc_u32 s101, s101, 0
	s_lshr_b32 s97, s33, 3
	s_and_b32 s97, s97, 3
	s_lshl_b32 s97, s97, 11
	v_mbcnt_lo_u32_b32 v240, -1, 0
	v_mbcnt_hi_u32_b32 v240, -1, v240
	v_lshrrev_b32_e32 v241, 2, v240
	v_and_b32_e32 v242, 3, v240
	v_lshlrev_b32_e32 v241, 7, v241
	v_lshl_add_u32 v241, v242, 5, v241
	v_add_u32_e32 v242, s97, v241
	s_add_i32 s97, s97, 0x800
	s_and_b32 s97, s97, 0x1800
	v_add_u32_e32 v241, s97, v241
	v_mov_b32_e32 v244, 0
	s_mov_b32 s32, 5
.Lscan_h_loop:
	ds_read_b32 v243, v244
	s_waitcnt lgkmcnt(0)
	v_readfirstlane_b32 s96, v243
	s_add_i32 s96, s96, 14
	s_min_u32 s96, s96, 0x80
.Lscan_h_issue:
	s_cmp_ge_u32 s32, s96
	s_cbranch_scc1 .Lscan_h_wait
	global_load_dword v245, v242, s[98:99]
	global_load_dword v247, v241, s[100:101]
	s_add_u32 s98, s98, 0x2000
	s_addc_u32 s99, s99, 0
	s_add_u32 s100, s100, 0x2000
	s_addc_u32 s101, s101, 0
	s_add_i32 s32, s32, 1
	s_waitcnt vmcnt(56)
	s_branch .Lscan_h_issue
.Lscan_h_wait:
	s_cmp_ge_u32 s32, 0x80
	s_cbranch_scc1 .Lscan_h_done
	s_sleep 6
	s_branch .Lscan_h_loop
.Lscan_h_done:
	s_waitcnt vmcnt(0)
.LBB0_440:
	s_waitcnt vmcnt(0)
	s_waitcnt lgkmcnt(0)
	s_barrier
	s_and_saveexec_b64 s[0:1], s[34:35]
	s_cbranch_execz .LBB0_492
	s_add_i32 s2, 0, 0x12700
	v_mov_b32_e32 v2, s2
	s_waitcnt vmcnt(0) expcnt(0) lgkmcnt(0)
	ds_read_b32 v4, v2
	s_add_i32 s2, 0, 0x12704
	v_mov_b32_e32 v2, s2
	ds_read_b32 v2, v2
	s_waitcnt lgkmcnt(1)
	v_cmp_ne_u32_e32 vcc, 0, v4
	s_cbranch_vccnz .LBB0_456
	v_readlane_b32 s4, v236, 5
	v_readlane_b32 s5, v236, 6
	s_load_dwordx2 s[2:3], s[4:5], 0x4
	s_add_u32 s4, s54, 0xfc14a00
	s_addc_u32 s5, s55, 0
	s_add_u32 s6, s54, 0xfc14c00
	s_addc_u32 s7, s55, 0
	s_add_u32 s8, s54, 0xfc14d00
	s_addc_u32 s9, s55, 0
	s_add_u32 s10, s54, 0xfc14e00
	s_addc_u32 s11, s55, 0
	s_add_u32 s12, s54, 0xfc14f00
	s_addc_u32 s13, s55, 0
	s_add_u32 s14, s54, 0xfc15000
	s_addc_u32 s15, s55, 0
	s_add_u32 s16, s54, 0xfc15100
	s_addc_u32 s17, s55, 0
	s_add_u32 s18, s54, 0xfc15200
	s_addc_u32 s19, s55, 0
	s_add_u32 s20, s54, 0xfc15300
	s_addc_u32 s21, s55, 0
	s_add_u32 s22, s54, 0xfc15400
	s_addc_u32 s23, s55, 0
	s_add_u32 s24, s54, 0xfc15500
	s_addc_u32 s25, s55, 0
	s_add_u32 s26, s54, 0xfc15600
	s_addc_u32 s27, s55, 0
	s_add_u32 s28, s54, 0xfc15700
	s_addc_u32 s29, s55, 0
	s_add_u32 s30, s54, 0xfc15800
	s_addc_u32 s31, s55, 0
	s_add_u32 s36, s54, 0xfc15900
	s_addc_u32 s37, s55, 0
	s_add_u32 s40, s54, 0xfc15a00
	s_addc_u32 s41, s55, 0
	s_waitcnt lgkmcnt(0)
	s_mul_i32 s33, s2, s95
	s_add_u32 s42, s54, 0xfc15b00
	s_mul_i32 s33, s33, s3
	s_addc_u32 s43, s55, 0
	s_mov_b32 s38, 1
	v_mov_b32_e32 v18, 0
	s_branch .LBB0_444

; extern "C" __global__ void __launch_bounds__(256, 2) hymba_mega(Params p, int ph_lo, int ph_hi) {
;     extern __shared__ __attribute__((aligned(16))) char lds[];
	.amdhsa_kernel hymba_mega
		.amdhsa_group_segment_fixed_size 0
		.amdhsa_private_segment_fixed_size 0
		.amdhsa_kernarg_size 456
		.amdhsa_user_sgpr_count 2
		.amdhsa_user_sgpr_dispatch_ptr 0
		.amdhsa_user_sgpr_queue_ptr 0
		.amdhsa_user_sgpr_kernarg_segment_ptr 1
		.amdhsa_user_sgpr_dispatch_id 0
		.amdhsa_user_sgpr_kernarg_preload_length 0
		.amdhsa_user_sgpr_kernarg_preload_offset 0
		.amdhsa_user_sgpr_private_segment_size 0
		.amdhsa_uses_dynamic_stack 0
		.amdhsa_enable_private_segment 0
		.amdhsa_system_sgpr_workgroup_id_x 1
		.amdhsa_system_sgpr_workgroup_id_y 0
		.amdhsa_system_sgpr_workgroup_id_z 0
		.amdhsa_system_sgpr_workgroup_info 0
		.amdhsa_system_vgpr_workitem_id 0
		.amdhsa_next_free_vgpr 256
		.amdhsa_next_free_sgpr 102
		.amdhsa_accum_offset 256
		.amdhsa_reserve_vcc 1
		.amdhsa_float_round_mode_32 0
		.amdhsa_float_round_mode_16_64 0
		.amdhsa_float_denorm_mode_32 3
		.amdhsa_float_denorm_mode_16_64 3
		.amdhsa_dx10_clamp 1
		.amdhsa_ieee_mode 1
		.amdhsa_fp16_overflow 0
		.amdhsa_tg_split 0
		.amdhsa_exception_fp_ieee_invalid_op 0
		.amdhsa_exception_fp_denorm_src 0
		.amdhsa_exception_fp_ieee_div_zero 0
		.amdhsa_exception_fp_ieee_overflow 0
		.amdhsa_exception_fp_ieee_underflow 0
		.amdhsa_exception_fp_ieee_inexact 0
		.amdhsa_exception_int_div_zero 0
	.end_amdhsa_kernel

; extern "C" __global__ void __launch_bounds__(256, 2) hymba_mega(Params p, int ph_lo, int ph_hi) {
;     extern __shared__ __attribute__((aligned(16))) char lds[];
amdhsa.kernels:
  - .agpr_count:     0
    .args:
      - .offset:         0
        .size:           192
        .value_kind:     by_value
      - .offset:         192
        .size:           4
        .value_kind:     by_value
      - .offset:         196
        .size:           4
        .value_kind:     by_value
      - .offset:         200
        .size:           4
        .value_kind:     hidden_block_count_x
      - .offset:         204
        .size:           4
        .value_kind:     hidden_block_count_y
      - .offset:         208
        .size:           4
        .value_kind:     hidden_block_count_z
      - .offset:         212
        .size:           2
        .value_kind:     hidden_group_size_x
      - .offset:         214
        .size:           2
        .value_kind:     hidden_group_size_y
      - .offset:         216
        .size:           2
        .value_kind:     hidden_group_size_z
      - .offset:         218
        .size:           2
        .value_kind:     hidden_remainder_x
      - .offset:         220
        .size:           2
        .value_kind:     hidden_remainder_y
      - .offset:         222
        .size:           2
        .value_kind:     hidden_remainder_z
      - .offset:         240
        .size:           8
        .value_kind:     hidden_global_offset_x
      - .offset:         248
        .size:           8
        .value_kind:     hidden_global_offset_y
      - .offset:         256
        .size:           8
        .value_kind:     hidden_global_offset_z
      - .offset:         264
        .size:           2
        .value_kind:     hidden_grid_dims
      - .offset:         320
        .size:           4
        .value_kind:     hidden_dynamic_lds_size
    .group_segment_fixed_size: 0
    .kernarg_segment_align: 8
    .kernarg_segment_size: 456
    .language:       OpenCL C
    .language_version:
      - 2
      - 0
    .max_flat_workgroup_size: 256
    .name:           hymba_mega
    .private_segment_fixed_size: 0
    .sgpr_count:     108
    .sgpr_spill_count: 70
    .symbol:         hymba_mega.kd
    .uniform_work_group_size: 1
    .uses_dynamic_stack: false
    .vgpr_count:     256
    .vgpr_spill_count: 0
    .wavefront_size: 64
